# nt (streaming) hint on the 16 coalesced full-line retention-state stores (probe: -16 us per phase warm)
# baseline (speedup 1.0000x reference)
; #define LAS __attribute__((address_space(3)))
; __device__ __forceinline__ unsigned cvt_pk_bf16(float lo, float hi) { f32x2 v = {lo, hi}; bf16x2_t b = __builtin_convertvector(v, bf16x2_t); return __builtin_bit_cast(unsigned, b); }
; __device__ __forceinline__ float bf_lo(unsigned u) { return __uint_as_float(u << 16); }
; __device__ __forceinline__ float bf_hi(unsigned u) { return __uint_as_float(u & 0xffff0000u); }
; __device__ void ret_state_item(const bf16_t* __restrict__ Kb, const bf16_t* __restrict__ Vb, bf16_t* __restrict__ STf, bf16_t* __restrict__ STb,
;                                int cidx, int head, float lgf2, float lgb2, LAS unsigned char* lds) {
;     ...
;   for (int it = 0; it < 8; ++it) { const int q = tid + it * 512, j = q >> 5, c = q & 31;
;     *(LAS u32x4*)(lds + j * VS + c * 16) = *(const u32x4*)(Vb + (size_t)(row0 + j) * 1024 + head * 256 + c * 8); }
; #pragma unroll
;   for (int it = 0; it < 4; ++it) { const int q = tid + it * 512, j = q >> 4, c = q & 15;
;     const u32x4 v = *(const u32x4*)(Kb + (size_t)(row0 + j) * 512 + head * 128 + c * 8);
;     const float zf = __builtin_amdgcn_exp2f(lgf2 * (float)(127 - j)), zb = __builtin_amdgcn_exp2f(lgb2 * (float)j);
;     u32x4 of, ob;
; #pragma unroll
;     for (int i = 0; i < 4; ++i) { const float a = bf_lo(v[i]), b = bf_hi(v[i]); of[i] = cvt_pk_bf16(a * zf, b * zf); ob[i] = cvt_pk_bf16(a * zb, b * zb); }
;     *(LAS u32x4*)(lds + OKF + j * KS + c * 16) = of; *(LAS u32x4*)(lds + OKB + j * KS + c * 16) = ob; }
.LBB0_437:
	v_mov_b32_e32 v152, v214
	s_and_b32 s12, s6, 0xffffff80
	s_lshl_b32 s20, s13, 8
	s_lshl_b32 s13, s13, 9
	v_ashrrev_i32_e32 v13, 5, v152
	v_and_b32_e32 v153, 31, v152
	s_add_u32 s34, s14, s13
	v_add_u32_e32 v2, s12, v13
	s_addc_u32 s35, s15, 0
	v_lshlrev_b32_e32 v160, 4, v153
	v_ashrrev_i32_e32 v3, 31, v2
	v_lshl_add_u64 v[0:1], s[34:35], 0, v[160:161]
	v_lshlrev_b64 v[2:3], 11, v[2:3]
	v_add_u32_e32 v47, 0x200, v152
	v_lshl_add_u64 v[2:3], v[0:1], 0, v[2:3]
	v_ashrrev_i32_e32 v50, 5, v47
	global_load_dwordx4 v[14:17], v[2:3], off
	v_add_u32_e32 v2, s12, v50
	v_ashrrev_i32_e32 v3, 31, v2
	v_lshlrev_b64 v[2:3], 11, v[2:3]
	v_add_u32_e32 v52, 0x400, v152
	v_lshl_add_u64 v[2:3], v[0:1], 0, v[2:3]
	v_ashrrev_i32_e32 v53, 5, v52
	global_load_dwordx4 v[18:21], v[2:3], off
	v_add_u32_e32 v2, s12, v53
	v_ashrrev_i32_e32 v3, 31, v2
	v_lshlrev_b64 v[2:3], 11, v[2:3]
	v_add_u32_e32 v12, 0x600, v152
	v_lshl_add_u64 v[2:3], v[0:1], 0, v[2:3]
	v_ashrrev_i32_e32 v54, 5, v12
	global_load_dwordx4 v[22:25], v[2:3], off
	v_add_u32_e32 v2, s12, v54
	v_ashrrev_i32_e32 v3, 31, v2
	v_lshlrev_b64 v[2:3], 11, v[2:3]
	v_lshl_add_u64 v[2:3], v[0:1], 0, v[2:3]
	global_load_dwordx4 v[26:29], v[2:3], off
	v_add_u32_e32 v2, 0x800, v152
	v_ashrrev_i32_e32 v55, 5, v2
	v_add_u32_e32 v2, s12, v55
	v_ashrrev_i32_e32 v3, 31, v2
	v_lshlrev_b64 v[2:3], 11, v[2:3]
	v_lshl_add_u64 v[2:3], v[0:1], 0, v[2:3]
	global_load_dwordx4 v[30:33], v[2:3], off
	v_add_u32_e32 v2, 0xa00, v152
	v_ashrrev_i32_e32 v56, 5, v2
	v_add_u32_e32 v2, s12, v56
	v_ashrrev_i32_e32 v3, 31, v2
	v_lshlrev_b64 v[2:3], 11, v[2:3]
	v_lshl_add_u64 v[2:3], v[0:1], 0, v[2:3]
	global_load_dwordx4 v[34:37], v[2:3], off
	v_add_u32_e32 v2, 0xc00, v152
	v_ashrrev_i32_e32 v57, 5, v2
	v_add_u32_e32 v2, s12, v57
	v_ashrrev_i32_e32 v3, 31, v2
	v_lshlrev_b64 v[2:3], 11, v[2:3]
	v_lshl_add_u64 v[2:3], v[0:1], 0, v[2:3]
	global_load_dwordx4 v[38:41], v[2:3], off
	v_add_u32_e32 v2, 0xe00, v152
	v_ashrrev_i32_e32 v58, 5, v2
	v_add_u32_e32 v2, s12, v58
	v_ashrrev_i32_e32 v3, 31, v2
	v_lshlrev_b64 v[2:3], 11, v[2:3]
	v_lshl_add_u64 v[0:1], v[0:1], 0, v[2:3]
	global_load_dwordx4 v[42:45], v[0:1], off
	v_lshlrev_b32_e32 v0, 4, v152
	v_ashrrev_i32_e32 v59, 4, v152
	v_add_u32_e32 v46, 0, v160
	s_add_u32 s34, s52, s20
	v_and_b32_e32 v160, 0xf0, v0
	v_add_u32_e32 v0, s12, v59
	s_addc_u32 s35, s62, 0
	v_ashrrev_i32_e32 v1, 31, v0
	v_lshl_add_u64 v[8:9], s[34:35], 0, v[160:161]
	v_lshlrev_b64 v[0:1], 10, v[0:1]
	v_lshl_add_u64 v[0:1], v[8:9], 0, v[0:1]
	global_load_dwordx4 v[4:7], v[0:1], off
	v_ashrrev_i32_e32 v47, 4, v47
	v_add_u32_e32 v0, s12, v47
	v_ashrrev_i32_e32 v1, 31, v0
	v_lshlrev_b64 v[0:1], 10, v[0:1]
	v_lshl_add_u64 v[0:1], v[8:9], 0, v[0:1]
	global_load_dwordx4 v[0:3], v[0:1], off
	v_ashrrev_i32_e32 v190, 4, v52
	v_add_u32_e32 v190, s12, v190
	v_ashrrev_i32_e32 v191, 31, v190
	v_lshlrev_b64 v[190:191], 10, v[190:191]
	v_lshl_add_u64 v[190:191], v[8:9], 0, v[190:191]
	global_load_dwordx4 v[182:185], v[190:191], off
	v_ashrrev_i32_e32 v190, 4, v12
	v_add_u32_e32 v190, s12, v190
	v_ashrrev_i32_e32 v191, 31, v190
	v_lshlrev_b64 v[190:191], 10, v[190:191]
	v_lshl_add_u64 v[190:191], v[8:9], 0, v[190:191]
	global_load_dwordx4 v[186:189], v[190:191], off
	v_mad_u64_u32 v[48:49], s[34:35], v13, s54, v[46:47]
	v_mad_u64_u32 v[50:51], s[34:35], v50, s54, v[46:47]
	v_sub_u32_e32 v13, 0x7f, v59
	v_cvt_f32_i32_e32 v13, v13
	s_waitcnt vmcnt(11)
	ds_write_b128 v48, v[14:17]
	s_waitcnt vmcnt(10)
	ds_write_b128 v50, v[18:21]
	v_mad_u64_u32 v[14:15], s[34:35], v53, s54, v[46:47]
	v_mul_f32_e32 v13, v10, v13
	s_add_i32 s13, 0, 0x12000
	s_add_i32 s7, s7, s90
	s_waitcnt vmcnt(9)
	ds_write_b128 v14, v[22:25]
	v_mad_u64_u32 v[14:15], s[34:35], v54, s54, v[46:47]
	v_exp_f32_e32 v22, v13
	v_add_u32_e32 v25, s13, v160
	s_waitcnt vmcnt(8)
	ds_write_b128 v14, v[26:29]
	v_mad_u64_u32 v[14:15], s[34:35], v55, s54, v[46:47]
	v_ashrrev_i32_e32 v29, 4, v52
	s_add_i32 s13, 0, 0x1c000
	v_add_u32_e32 v28, s13, v160
	s_movk_i32 s13, 0x140
	s_waitcnt vmcnt(7)
	ds_write_b128 v14, v[30:33]
	v_mad_u64_u32 v[14:15], s[34:35], v56, s54, v[46:47]
	s_waitcnt vmcnt(6)
	ds_write_b128 v14, v[34:37]
	v_mad_u64_u32 v[14:15], s[34:35], v57, s54, v[46:47]
	s_waitcnt vmcnt(5)
	ds_write_b128 v14, v[38:41]
	v_mad_u64_u32 v[14:15], s[34:35], v58, s54, v[46:47]
	s_waitcnt vmcnt(4)
	ds_write_b128 v14, v[42:45]
	v_cvt_f32_i32_e32 v14, v59
	v_mul_f32_e32 v13, v11, v14
	v_exp_f32_e32 v24, v13
	s_waitcnt vmcnt(3)
	v_lshlrev_b32_e32 v18, 16, v4
	v_and_b32_e32 v19, 0xffff0000, v4
	v_pk_mul_f32 v[20:21], v[22:23], v[18:19] op_sel_hi:[0,1]
	v_cvt_pk_bf16_f32 v4, v20, v21
	v_lshlrev_b32_e32 v20, 16, v5
	v_and_b32_e32 v21, 0xffff0000, v5
	v_pk_mul_f32 v[18:19], v[24:25], v[18:19] op_sel_hi:[0,1]
	v_pk_mul_f32 v[26:27], v[22:23], v[20:21] op_sel_hi:[0,1]
	v_pk_mul_f32 v[20:21], v[24:25], v[20:21] op_sel_hi:[0,1]
	v_cvt_pk_bf16_f32 v18, v18, v19
	v_cvt_pk_bf16_f32 v19, v20, v21
	v_lshlrev_b32_e32 v20, 16, v6
	v_and_b32_e32 v21, 0xffff0000, v6
	v_cvt_pk_bf16_f32 v5, v26, v27
	v_pk_mul_f32 v[26:27], v[22:23], v[20:21] op_sel_hi:[0,1]
	v_cvt_pk_bf16_f32 v6, v26, v27
	v_lshlrev_b32_e32 v26, 16, v7
	v_and_b32_e32 v27, 0xffff0000, v7
	v_pk_mul_f32 v[22:23], v[22:23], v[26:27] op_sel_hi:[0,1]
	v_pk_mul_f32 v[20:21], v[24:25], v[20:21] op_sel_hi:[0,1]
	v_cvt_pk_bf16_f32 v7, v22, v23
	v_pk_mul_f32 v[22:23], v[24:25], v[26:27] op_sel_hi:[0,1]
	v_mul_lo_u32 v13, v59, s13
	v_cvt_pk_bf16_f32 v20, v20, v21
	v_cvt_pk_bf16_f32 v21, v22, v23
	v_add_u32_e32 v22, v25, v13
	ds_write_b128 v22, v[4:7]
	v_sub_u32_e32 v4, 0x7f, v47
	v_ashrrev_i32_e32 v24, 4, v12
	v_cvt_f32_i32_e32 v22, v4
	v_cvt_f32_i32_e32 v9, v47
	v_add_u32_e32 v8, v28, v13
	ds_write_b128 v8, v[18:21]
	v_mul_f32_e32 v8, v10, v22
	v_exp_f32_e32 v8, v8
	v_mul_f32_e32 v9, v11, v9
	v_exp_f32_e32 v12, v9
	s_waitcnt vmcnt(2)
; #define LAS __attribute__((address_space(3)))
; __device__ __forceinline__ unsigned cvt_pk_bf16(float lo, float hi) { f32x2 v = {lo, hi}; bf16x2_t b = __builtin_convertvector(v, bf16x2_t); return __builtin_bit_cast(unsigned, b); }
; __device__ __forceinline__ float bf_lo(unsigned u) { return __uint_as_float(u << 16); }
; __device__ __forceinline__ float bf_hi(unsigned u) { return __uint_as_float(u & 0xffff0000u); }
; __device__ void ret_state_item(const bf16_t* __restrict__ Kb, const bf16_t* __restrict__ Vb, bf16_t* __restrict__ STf, bf16_t* __restrict__ STb,
;                                int cidx, int head, float lgf2, float lgb2, LAS unsigned char* lds) {
;     ...
;   for (int it = 0; it < 4; ++it) { const int q = tid + it * 512, j = q >> 4, c = q & 15;
;     const u32x4 v = *(const u32x4*)(Kb + (size_t)(row0 + j) * 512 + head * 128 + c * 8);
;     const float zf = __builtin_amdgcn_exp2f(lgf2 * (float)(127 - j)), zb = __builtin_amdgcn_exp2f(lgb2 * (float)j);
;     u32x4 of, ob;
; #pragma unroll
;     for (int i = 0; i < 4; ++i) { const float a = bf_lo(v[i]), b = bf_hi(v[i]); of[i] = cvt_pk_bf16(a * zf, b * zf); ob[i] = cvt_pk_bf16(a * zb, b * zb); }
;     *(LAS u32x4*)(lds + OKF + j * KS + c * 16) = of; *(LAS u32x4*)(lds + OKB + j * KS + c * 16) = ob; }
;   __syncthreads();
;   const int i16 = l & 15, q4 = i16 >> 2, p4 = i16 & 3, G1 = (l >> 4) & 1, h = l >> 5;
;   const unsigned cofs = (unsigned)(16 * G1 + 4 * p4) * 2u;
;   f32x16 af[4], ab[4];
; #pragma unroll
;   for (int i = 0; i < 4; ++i) { af[i] = (f32x16){}; ab[i] = (f32x16){}; }
;   for (int ks = 0; ks < 8; ++ks) {
;     const unsigned r = (unsigned)(16 * ks + 8 * h + q4);
;     const bf16x8 Bv = tr_frag(lds, r * VS + w * 64 + cofs, (r + 4) * VS + w * 64 + cofs);
	v_lshlrev_b32_e32 v18, 16, v0
	v_and_b32_e32 v19, 0xffff0000, v0
	v_pk_mul_f32 v[20:21], v[8:9], v[18:19] op_sel_hi:[0,1]
	v_cvt_pk_bf16_f32 v0, v20, v21
	v_lshlrev_b32_e32 v20, 16, v1
	v_and_b32_e32 v21, 0xffff0000, v1
	v_pk_mul_f32 v[18:19], v[12:13], v[18:19] op_sel_hi:[0,1]
	v_pk_mul_f32 v[22:23], v[8:9], v[20:21] op_sel_hi:[0,1]
	v_pk_mul_f32 v[20:21], v[12:13], v[20:21] op_sel_hi:[0,1]
	v_cvt_pk_bf16_f32 v18, v18, v19
	v_cvt_pk_bf16_f32 v19, v20, v21
	v_lshlrev_b32_e32 v20, 16, v2
	v_and_b32_e32 v21, 0xffff0000, v2
	v_cvt_pk_bf16_f32 v1, v22, v23
	v_pk_mul_f32 v[22:23], v[8:9], v[20:21] op_sel_hi:[0,1]
	v_cvt_pk_bf16_f32 v2, v22, v23
	v_lshlrev_b32_e32 v22, 16, v3
	v_and_b32_e32 v23, 0xffff0000, v3
	v_pk_mul_f32 v[8:9], v[8:9], v[22:23] op_sel_hi:[0,1]
	v_pk_mul_f32 v[20:21], v[12:13], v[20:21] op_sel_hi:[0,1]
	v_cvt_pk_bf16_f32 v3, v8, v9
	v_pk_mul_f32 v[8:9], v[12:13], v[22:23] op_sel_hi:[0,1]
	v_cvt_pk_bf16_f32 v20, v20, v21
	v_cvt_pk_bf16_f32 v21, v8, v9
	v_mul_lo_u32 v8, v47, s13
	v_add_u32_e32 v9, v25, v8
	ds_write_b128 v9, v[0:3]
	v_sub_u32_e32 v0, 0x7f, v29
	v_cvt_f32_i32_e32 v0, v0
	v_cvt_f32_i32_e32 v2, v29
	v_add_u32_e32 v1, v28, v8
	ds_write_b128 v1, v[18:21]
	v_mul_f32_e32 v0, v10, v0
	v_exp_f32_e32 v8, v0
	v_mul_f32_e32 v0, v11, v2
	v_exp_f32_e32 v18, v0
	s_waitcnt vmcnt(1)
	v_mov_b64_e32 v[14:15], v[182:183]
	v_mov_b64_e32 v[16:17], v[184:185]
	v_lshlrev_b32_e32 v2, 16, v14
	v_and_b32_e32 v3, 0xffff0000, v14
	v_pk_mul_f32 v[0:1], v[8:9], v[2:3] op_sel_hi:[0,1]
	v_pk_mul_f32 v[2:3], v[18:19], v[2:3] op_sel_hi:[0,1]
	v_cvt_pk_bf16_f32 v12, v2, v3
	v_lshlrev_b32_e32 v2, 16, v15
	v_and_b32_e32 v3, 0xffff0000, v15
	v_pk_mul_f32 v[14:15], v[8:9], v[2:3] op_sel_hi:[0,1]
	v_cvt_pk_bf16_f32 v0, v0, v1
	v_cvt_pk_bf16_f32 v1, v14, v15
	v_pk_mul_f32 v[2:3], v[18:19], v[2:3] op_sel_hi:[0,1]
	v_lshlrev_b32_e32 v14, 16, v16
	v_and_b32_e32 v15, 0xffff0000, v16
	v_lshlrev_b32_e32 v16, 16, v17
	v_and_b32_e32 v17, 0xffff0000, v17
	v_cvt_pk_bf16_f32 v13, v2, v3
	v_pk_mul_f32 v[2:3], v[8:9], v[14:15] op_sel_hi:[0,1]
	v_pk_mul_f32 v[8:9], v[8:9], v[16:17] op_sel_hi:[0,1]
	v_cvt_pk_bf16_f32 v2, v2, v3
	v_pk_mul_f32 v[14:15], v[18:19], v[14:15] op_sel_hi:[0,1]
	v_cvt_pk_bf16_f32 v3, v8, v9
	v_pk_mul_f32 v[8:9], v[18:19], v[16:17] op_sel_hi:[0,1]
	v_cvt_pk_bf16_f32 v14, v14, v15
	v_cvt_pk_bf16_f32 v15, v8, v9
	v_mul_lo_u32 v8, v29, s13
	v_add_u32_e32 v9, v25, v8
	ds_write_b128 v9, v[0:3]
	v_sub_u32_e32 v0, 0x7f, v24
	v_cvt_f32_i32_e32 v0, v0
	v_cvt_f32_i32_e32 v2, v24
	v_add_u32_e32 v1, v28, v8
	ds_write_b128 v1, v[12:15]
	v_mul_f32_e32 v0, v10, v0
	v_exp_f32_e32 v8, v0
	v_mul_f32_e32 v0, v11, v2
	v_exp_f32_e32 v10, v0
	s_waitcnt vmcnt(0)
	v_mov_b64_e32 v[4:5], v[186:187]
	v_mov_b64_e32 v[6:7], v[188:189]
	v_lshlrev_b32_e32 v2, 16, v4
	v_and_b32_e32 v3, 0xffff0000, v4
	v_pk_mul_f32 v[0:1], v[8:9], v[2:3] op_sel_hi:[0,1]
	v_pk_mul_f32 v[2:3], v[10:11], v[2:3] op_sel_hi:[0,1]
	v_cvt_pk_bf16_f32 v4, v2, v3
	v_lshlrev_b32_e32 v2, 16, v5
	v_and_b32_e32 v3, 0xffff0000, v5
	v_pk_mul_f32 v[12:13], v[8:9], v[2:3] op_sel_hi:[0,1]
	v_cvt_pk_bf16_f32 v0, v0, v1
	v_cvt_pk_bf16_f32 v1, v12, v13
	v_pk_mul_f32 v[2:3], v[10:11], v[2:3] op_sel_hi:[0,1]
	v_lshlrev_b32_e32 v12, 16, v6
	v_and_b32_e32 v13, 0xffff0000, v6
	v_cvt_pk_bf16_f32 v5, v2, v3
	v_pk_mul_f32 v[2:3], v[8:9], v[12:13] op_sel_hi:[0,1]
	v_pk_mul_f32 v[12:13], v[10:11], v[12:13] op_sel_hi:[0,1]
	v_cvt_pk_bf16_f32 v6, v12, v13
	v_lshlrev_b32_e32 v12, 16, v7
	v_and_b32_e32 v13, 0xffff0000, v7
	v_pk_mul_f32 v[8:9], v[8:9], v[12:13] op_sel_hi:[0,1]
	v_cvt_pk_bf16_f32 v2, v2, v3
	v_cvt_pk_bf16_f32 v3, v8, v9
	v_pk_mul_f32 v[8:9], v[10:11], v[12:13] op_sel_hi:[0,1]
	v_cvt_pk_bf16_f32 v7, v8, v9
	v_mul_lo_u32 v8, v24, s13
	v_add_u32_e32 v9, v25, v8
	ds_write_b128 v9, v[0:3]
	v_add_u32_e32 v0, v28, v8
	ds_write_b128 v0, v[4:7]
	v_lshrrev_b32_e32 v0, 2, v152
	v_and_b32_e32 v1, 16, v152
	v_lshlrev_b32_e32 v2, 2, v152
	v_and_or_b32 v1, v2, 12, v1
	v_and_b32_e32 v5, 11, v0
	v_and_b32_e32 v0, 0xffffffc0, v152
	v_lshlrev_b32_e32 v4, 1, v1
	v_add_u32_e32 v6, 0, v0
	v_mul_u32_u24_e32 v0, 0x140, v5
	v_add3_u32 v154, 0, v0, v4
	v_mul_u32_u24_e32 v5, 0x240, v5
	v_add_u32_e32 v12, 0x12000, v154
	v_add3_u32 v132, v6, v4, v5
	v_add_u32_e32 v14, 0x1c000, v154
	v_add_u32_e32 v15, 0x1c500, v154
	s_waitcnt lgkmcnt(0)
	s_barrier
; __device__ __forceinline__ f32x16 mfma32(bf16x8 a, bf16x8 b, f32x16 c) { return __builtin_amdgcn_mfma_f32_32x32x16_bf16(a, b, c, 0, 0, 0); }
; __device__ void ret_state_item(const bf16_t* __restrict__ Kb, const bf16_t* __restrict__ Vb, bf16_t* __restrict__ STf, bf16_t* __restrict__ STb,
;                                int cidx, int head, float lgf2, float lgb2, LAS unsigned char* lds) {
;     ...
;   for (int ks = 0; ks < 8; ++ks) {
;     const unsigned r = (unsigned)(16 * ks + 8 * h + q4);
;     const bf16x8 Bv = tr_frag(lds, r * VS + w * 64 + cofs, (r + 4) * VS + w * 64 + cofs);
; #pragma unroll
;     for (int dt = 0; dt < 4; ++dt) {
;       const bf16x8 Af = tr_frag(lds, OKF + r * KS + dt * 64 + cofs, OKF + (r + 4) * KS + dt * 64 + cofs);
;       const bf16x8 Ab = tr_frag(lds, OKB + r * KS + dt * 64 + cofs, OKB + (r + 4) * KS + dt * 64 + cofs);
;       af[dt] = mfma32(Af, Bv, af[dt]); ab[dt] = mfma32(Ab, Bv, ab[dt]);
;     }
;   }
	v_add_u32_e32 v13, 0x12500, v154
	ds_read_b64_tr_b16 v[0:1], v12
	ds_read_b64_tr_b16 v[2:3], v13
	ds_read_b64_tr_b16 v[4:5], v132
	ds_read_b64_tr_b16 v[6:7], v132 offset:2304
	ds_read_b64_tr_b16 v[8:9], v14
	ds_read_b64_tr_b16 v[10:11], v15
	s_waitcnt lgkmcnt(2)
	v_mfma_f32_32x32x16_bf16 v[112:127], v[0:3], v[4:7], 0
	v_add_u32_e32 v133, 0x13400, v154
	v_add_u32_e32 v135, 0x1d400, v154
	v_add_u32_e32 v155, 0x1d900, v154
	v_add_u32_e32 v134, 0x13900, v154
	v_readlane_b32 s12, v250, 51
	v_readlane_b32 s13, v250, 52
	s_waitcnt lgkmcnt(0)
	v_mfma_f32_32x32x16_bf16 v[96:111], v[8:11], v[4:7], 0
	ds_read_b64_tr_b16 v[0:1], v12 offset:64
	ds_read_b64_tr_b16 v[2:3], v13 offset:64
	ds_read_b64_tr_b16 v[8:9], v14 offset:64
	ds_read_b64_tr_b16 v[10:11], v15 offset:64
	s_waitcnt lgkmcnt(2)
	v_mfma_f32_32x32x16_bf16 v[80:95], v[0:3], v[4:7], 0
	s_waitcnt lgkmcnt(0)
	v_mfma_f32_32x32x16_bf16 v[64:79], v[8:11], v[4:7], 0
	ds_read_b64_tr_b16 v[0:1], v12 offset:128
	ds_read_b64_tr_b16 v[2:3], v13 offset:128
	ds_read_b64_tr_b16 v[8:9], v14 offset:128
	ds_read_b64_tr_b16 v[10:11], v15 offset:128
	s_waitcnt lgkmcnt(2)
	v_mfma_f32_32x32x16_bf16 v[48:63], v[0:3], v[4:7], 0
	s_waitcnt lgkmcnt(0)
	v_mfma_f32_32x32x16_bf16 v[16:31], v[8:11], v[4:7], 0
	ds_read_b64_tr_b16 v[0:1], v12 offset:192
	ds_read_b64_tr_b16 v[2:3], v13 offset:192
	ds_read_b64_tr_b16 v[8:9], v14 offset:192
	ds_read_b64_tr_b16 v[10:11], v15 offset:192
	ds_read_b64_tr_b16 v[128:129], v133
	ds_read_b64_tr_b16 v[130:131], v134
	ds_read_b64_tr_b16 v[156:157], v132 offset:9216
	ds_read_b64_tr_b16 v[158:159], v132 offset:11520
	ds_read_b64_tr_b16 v[174:175], v135
	ds_read_b64_tr_b16 v[176:177], v155
	s_waitcnt lgkmcnt(2)
	v_mfma_f32_32x32x16_bf16 v[112:127], v[128:131], v[156:159], v[112:127]
	s_waitcnt lgkmcnt(0)
	v_mfma_f32_32x32x16_bf16 v[96:111], v[174:177], v[156:159], v[96:111]
	ds_read_b64_tr_b16 v[128:129], v133 offset:64
	ds_read_b64_tr_b16 v[130:131], v134 offset:64
	ds_read_b64_tr_b16 v[174:175], v135 offset:64
	ds_read_b64_tr_b16 v[176:177], v155 offset:64
	s_waitcnt lgkmcnt(2)
	v_mfma_f32_32x32x16_bf16 v[80:95], v[128:131], v[156:159], v[80:95]
	s_waitcnt lgkmcnt(0)
	v_mfma_f32_32x32x16_bf16 v[64:79], v[174:177], v[156:159], v[64:79]
	ds_read_b64_tr_b16 v[128:129], v133 offset:128
	ds_read_b64_tr_b16 v[130:131], v134 offset:128
	ds_read_b64_tr_b16 v[174:175], v135 offset:128
	ds_read_b64_tr_b16 v[176:177], v155 offset:128
	s_waitcnt lgkmcnt(2)
	v_mfma_f32_32x32x16_bf16 v[48:63], v[128:131], v[156:159], v[48:63]
	s_waitcnt lgkmcnt(0)
	v_mfma_f32_32x32x16_bf16 v[16:31], v[174:177], v[156:159], v[16:31]
	ds_read_b64_tr_b16 v[128:129], v133 offset:192
	ds_read_b64_tr_b16 v[130:131], v134 offset:192
	ds_read_b64_tr_b16 v[174:175], v135 offset:192
	ds_read_b64_tr_b16 v[176:177], v155 offset:192
	v_add_u32_e32 v133, 0x14800, v154
	v_add_u32_e32 v135, 0x1e800, v154
	v_add_u32_e32 v155, 0x1ed00, v154
	v_add_u32_e32 v134, 0x14d00, v154
	v_mfma_f32_32x32x16_bf16 v[32:47], v[0:3], v[4:7], 0
	v_mfma_f32_32x32x16_bf16 v[0:15], v[8:11], v[4:7], 0
	s_waitcnt lgkmcnt(2)
	v_mfma_f32_32x32x16_bf16 v[32:47], v[128:131], v[156:159], v[32:47]
	s_waitcnt lgkmcnt(0)
	v_mfma_f32_32x32x16_bf16 v[0:15], v[174:177], v[156:159], v[0:15]
	ds_read_b64_tr_b16 v[128:129], v133
	ds_read_b64_tr_b16 v[130:131], v134
	ds_read_b64_tr_b16 v[156:157], v132 offset:18432
	ds_read_b64_tr_b16 v[158:159], v132 offset:20736
	ds_read_b64_tr_b16 v[174:175], v135
	ds_read_b64_tr_b16 v[176:177], v155
	s_waitcnt lgkmcnt(2)
	v_mfma_f32_32x32x16_bf16 v[112:127], v[128:131], v[156:159], v[112:127]
	s_waitcnt lgkmcnt(0)
	v_mfma_f32_32x32x16_bf16 v[96:111], v[174:177], v[156:159], v[96:111]
	ds_read_b64_tr_b16 v[128:129], v133 offset:64
	ds_read_b64_tr_b16 v[130:131], v134 offset:64
	ds_read_b64_tr_b16 v[174:175], v135 offset:64
	ds_read_b64_tr_b16 v[176:177], v155 offset:64
	s_waitcnt lgkmcnt(2)
	v_mfma_f32_32x32x16_bf16 v[80:95], v[128:131], v[156:159], v[80:95]
	s_waitcnt lgkmcnt(0)
	v_mfma_f32_32x32x16_bf16 v[64:79], v[174:177], v[156:159], v[64:79]
	ds_read_b64_tr_b16 v[128:129], v133 offset:128
	ds_read_b64_tr_b16 v[130:131], v134 offset:128
	ds_read_b64_tr_b16 v[174:175], v135 offset:128
	ds_read_b64_tr_b16 v[176:177], v155 offset:128
	s_waitcnt lgkmcnt(2)
	v_mfma_f32_32x32x16_bf16 v[48:63], v[128:131], v[156:159], v[48:63]
	s_waitcnt lgkmcnt(0)
	v_mfma_f32_32x32x16_bf16 v[16:31], v[174:177], v[156:159], v[16:31]
	ds_read_b64_tr_b16 v[128:129], v133 offset:192
	ds_read_b64_tr_b16 v[130:131], v134 offset:192
	ds_read_b64_tr_b16 v[174:175], v135 offset:192
	ds_read_b64_tr_b16 v[176:177], v155 offset:192
	v_add_u32_e32 v133, 0x15c00, v154
	v_add_u32_e32 v135, 0x1fc00, v154
	v_add_u32_e32 v155, 0x20100, v154
	v_add_u32_e32 v134, 0x16100, v154
	s_waitcnt lgkmcnt(2)
	v_mfma_f32_32x32x16_bf16 v[32:47], v[128:131], v[156:159], v[32:47]
	s_waitcnt lgkmcnt(0)
	v_mfma_f32_32x32x16_bf16 v[0:15], v[174:177], v[156:159], v[0:15]
	ds_read_b64_tr_b16 v[128:129], v133
	ds_read_b64_tr_b16 v[130:131], v134
	ds_read_b64_tr_b16 v[156:157], v132 offset:27648
	ds_read_b64_tr_b16 v[158:159], v132 offset:29952
	ds_read_b64_tr_b16 v[174:175], v135
	ds_read_b64_tr_b16 v[176:177], v155
	s_waitcnt lgkmcnt(2)
	v_mfma_f32_32x32x16_bf16 v[112:127], v[128:131], v[156:159], v[112:127]
	s_waitcnt lgkmcnt(0)
	v_mfma_f32_32x32x16_bf16 v[96:111], v[174:177], v[156:159], v[96:111]
	ds_read_b64_tr_b16 v[128:129], v133 offset:64
	ds_read_b64_tr_b16 v[130:131], v134 offset:64
	ds_read_b64_tr_b16 v[174:175], v135 offset:64
	ds_read_b64_tr_b16 v[176:177], v155 offset:64
	s_waitcnt lgkmcnt(2)
	v_mfma_f32_32x32x16_bf16 v[80:95], v[128:131], v[156:159], v[80:95]
	s_waitcnt lgkmcnt(0)
; __device__ __forceinline__ f32x16 mfma32(bf16x8 a, bf16x8 b, f32x16 c) { return __builtin_amdgcn_mfma_f32_32x32x16_bf16(a, b, c, 0, 0, 0); }
; __device__ void ret_state_item(const bf16_t* __restrict__ Kb, const bf16_t* __restrict__ Vb, bf16_t* __restrict__ STf, bf16_t* __restrict__ STb,
;                                int cidx, int head, float lgf2, float lgb2, LAS unsigned char* lds) {
;     ...
;   for (int ks = 0; ks < 8; ++ks) {
;     const unsigned r = (unsigned)(16 * ks + 8 * h + q4);
;     const bf16x8 Bv = tr_frag(lds, r * VS + w * 64 + cofs, (r + 4) * VS + w * 64 + cofs);
; #pragma unroll
;     for (int dt = 0; dt < 4; ++dt) {
;       const bf16x8 Af = tr_frag(lds, OKF + r * KS + dt * 64 + cofs, OKF + (r + 4) * KS + dt * 64 + cofs);
;       const bf16x8 Ab = tr_frag(lds, OKB + r * KS + dt * 64 + cofs, OKB + (r + 4) * KS + dt * 64 + cofs);
;       af[dt] = mfma32(Af, Bv, af[dt]); ab[dt] = mfma32(Ab, Bv, ab[dt]);
;     }
;   }
	v_mfma_f32_32x32x16_bf16 v[64:79], v[174:177], v[156:159], v[64:79]
	ds_read_b64_tr_b16 v[128:129], v133 offset:128
	ds_read_b64_tr_b16 v[130:131], v134 offset:128
	ds_read_b64_tr_b16 v[174:175], v135 offset:128
	ds_read_b64_tr_b16 v[176:177], v155 offset:128
	s_waitcnt lgkmcnt(2)
	v_mfma_f32_32x32x16_bf16 v[48:63], v[128:131], v[156:159], v[48:63]
	s_waitcnt lgkmcnt(0)
	v_mfma_f32_32x32x16_bf16 v[16:31], v[174:177], v[156:159], v[16:31]
	ds_read_b64_tr_b16 v[128:129], v133 offset:192
	ds_read_b64_tr_b16 v[130:131], v134 offset:192
	ds_read_b64_tr_b16 v[174:175], v135 offset:192
	ds_read_b64_tr_b16 v[176:177], v155 offset:192
	v_add_u32_e32 v133, 0x17000, v154
	v_add_u32_e32 v135, 0x21000, v154
	v_add_u32_e32 v155, 0x21500, v154
	v_add_u32_e32 v134, 0x17500, v154
	s_waitcnt lgkmcnt(2)
	v_mfma_f32_32x32x16_bf16 v[32:47], v[128:131], v[156:159], v[32:47]
	s_waitcnt lgkmcnt(0)
	v_mfma_f32_32x32x16_bf16 v[0:15], v[174:177], v[156:159], v[0:15]
	ds_read_b64_tr_b16 v[128:129], v133
	ds_read_b64_tr_b16 v[130:131], v134
	ds_read_b64_tr_b16 v[156:157], v132 offset:36864
	ds_read_b64_tr_b16 v[158:159], v132 offset:39168
	ds_read_b64_tr_b16 v[174:175], v135
	ds_read_b64_tr_b16 v[176:177], v155
	s_waitcnt lgkmcnt(2)
	v_mfma_f32_32x32x16_bf16 v[112:127], v[128:131], v[156:159], v[112:127]
	s_waitcnt lgkmcnt(0)
	v_mfma_f32_32x32x16_bf16 v[96:111], v[174:177], v[156:159], v[96:111]
	ds_read_b64_tr_b16 v[128:129], v133 offset:64
	ds_read_b64_tr_b16 v[130:131], v134 offset:64
	ds_read_b64_tr_b16 v[174:175], v135 offset:64
	ds_read_b64_tr_b16 v[176:177], v155 offset:64
	s_waitcnt lgkmcnt(2)
	v_mfma_f32_32x32x16_bf16 v[80:95], v[128:131], v[156:159], v[80:95]
	s_waitcnt lgkmcnt(0)
	v_mfma_f32_32x32x16_bf16 v[64:79], v[174:177], v[156:159], v[64:79]
	ds_read_b64_tr_b16 v[128:129], v133 offset:128
	ds_read_b64_tr_b16 v[130:131], v134 offset:128
	ds_read_b64_tr_b16 v[174:175], v135 offset:128
	ds_read_b64_tr_b16 v[176:177], v155 offset:128
	s_waitcnt lgkmcnt(2)
	v_mfma_f32_32x32x16_bf16 v[48:63], v[128:131], v[156:159], v[48:63]
	s_waitcnt lgkmcnt(0)
	v_mfma_f32_32x32x16_bf16 v[16:31], v[174:177], v[156:159], v[16:31]
	ds_read_b64_tr_b16 v[128:129], v133 offset:192
	ds_read_b64_tr_b16 v[130:131], v134 offset:192
	ds_read_b64_tr_b16 v[174:175], v135 offset:192
	ds_read_b64_tr_b16 v[176:177], v155 offset:192
	v_add_u32_e32 v133, 0x18400, v154
	v_add_u32_e32 v135, 0x22400, v154
	v_add_u32_e32 v155, 0x22900, v154
	v_add_u32_e32 v134, 0x18900, v154
	s_waitcnt lgkmcnt(2)
	v_mfma_f32_32x32x16_bf16 v[32:47], v[128:131], v[156:159], v[32:47]
	s_waitcnt lgkmcnt(0)
	v_mfma_f32_32x32x16_bf16 v[0:15], v[174:177], v[156:159], v[0:15]
	ds_read_b64_tr_b16 v[128:129], v133
	ds_read_b64_tr_b16 v[130:131], v134
	ds_read_b64_tr_b16 v[156:157], v132 offset:46080
	ds_read_b64_tr_b16 v[158:159], v132 offset:48384
	ds_read_b64_tr_b16 v[174:175], v135
	ds_read_b64_tr_b16 v[176:177], v155
	s_waitcnt lgkmcnt(2)
	v_mfma_f32_32x32x16_bf16 v[112:127], v[128:131], v[156:159], v[112:127]
	s_waitcnt lgkmcnt(0)
	v_mfma_f32_32x32x16_bf16 v[96:111], v[174:177], v[156:159], v[96:111]
	ds_read_b64_tr_b16 v[128:129], v133 offset:64
	ds_read_b64_tr_b16 v[130:131], v134 offset:64
	ds_read_b64_tr_b16 v[174:175], v135 offset:64
	ds_read_b64_tr_b16 v[176:177], v155 offset:64
	s_waitcnt lgkmcnt(2)
	v_mfma_f32_32x32x16_bf16 v[80:95], v[128:131], v[156:159], v[80:95]
	s_waitcnt lgkmcnt(0)
	v_mfma_f32_32x32x16_bf16 v[64:79], v[174:177], v[156:159], v[64:79]
	ds_read_b64_tr_b16 v[128:129], v133 offset:128
	ds_read_b64_tr_b16 v[130:131], v134 offset:128
	ds_read_b64_tr_b16 v[174:175], v135 offset:128
	ds_read_b64_tr_b16 v[176:177], v155 offset:128
	s_waitcnt lgkmcnt(2)
	v_mfma_f32_32x32x16_bf16 v[48:63], v[128:131], v[156:159], v[48:63]
	s_waitcnt lgkmcnt(0)
	v_mfma_f32_32x32x16_bf16 v[16:31], v[174:177], v[156:159], v[16:31]
	ds_read_b64_tr_b16 v[128:129], v133 offset:192
	ds_read_b64_tr_b16 v[130:131], v134 offset:192
	ds_read_b64_tr_b16 v[174:175], v135 offset:192
	ds_read_b64_tr_b16 v[176:177], v155 offset:192
	v_add_u32_e32 v133, 0x19800, v154
	v_add_u32_e32 v135, 0x23800, v154
	v_add_u32_e32 v155, 0x23d00, v154
	v_add_u32_e32 v134, 0x19d00, v154
	s_waitcnt lgkmcnt(2)
	v_mfma_f32_32x32x16_bf16 v[32:47], v[128:131], v[156:159], v[32:47]
	s_waitcnt lgkmcnt(0)
	v_mfma_f32_32x32x16_bf16 v[0:15], v[174:177], v[156:159], v[0:15]
	ds_read_b64_tr_b16 v[128:129], v133
	ds_read_b64_tr_b16 v[130:131], v134
	ds_read_b64_tr_b16 v[174:175], v132 offset:55296
	ds_read_b64_tr_b16 v[176:177], v132 offset:57600
	ds_read_b64_tr_b16 v[156:157], v135
	ds_read_b64_tr_b16 v[158:159], v155
	s_waitcnt lgkmcnt(2)
	v_mfma_f32_32x32x16_bf16 v[112:127], v[128:131], v[174:177], v[112:127]
	s_waitcnt lgkmcnt(0)
	v_mfma_f32_32x32x16_bf16 v[96:111], v[156:159], v[174:177], v[96:111]
	ds_read_b64_tr_b16 v[128:129], v133 offset:64
	ds_read_b64_tr_b16 v[130:131], v134 offset:64
	ds_read_b64_tr_b16 v[156:157], v135 offset:64
	ds_read_b64_tr_b16 v[158:159], v155 offset:64
	s_waitcnt lgkmcnt(2)
	v_mfma_f32_32x32x16_bf16 v[80:95], v[128:131], v[174:177], v[80:95]
	s_waitcnt lgkmcnt(0)
	v_mfma_f32_32x32x16_bf16 v[64:79], v[156:159], v[174:177], v[64:79]
	ds_read_b64_tr_b16 v[128:129], v133 offset:128
	ds_read_b64_tr_b16 v[130:131], v134 offset:128
	ds_read_b64_tr_b16 v[156:157], v135 offset:128
	ds_read_b64_tr_b16 v[158:159], v155 offset:128
	s_waitcnt lgkmcnt(2)
	v_mfma_f32_32x32x16_bf16 v[48:63], v[128:131], v[174:177], v[48:63]
	ds_read_b64_tr_b16 v[128:129], v133 offset:192
	ds_read_b64_tr_b16 v[130:131], v134 offset:192
	ds_read_b64_tr_b16 v[178:179], v135 offset:192
	ds_read_b64_tr_b16 v[180:181], v155 offset:192
	v_add_u32_e32 v134, 0x900, v132
	v_add_u32_e32 v155, 0x1b100, v154
	s_waitcnt lgkmcnt(4)
; __device__ __forceinline__ u32x2 pack4(float a, float b, float c, float d) { u32x2 o; o[0] = cvt_pk_bf16(a, b); o[1] = cvt_pk_bf16(c, d); return o; }
; __device__ __forceinline__ f32x16 mfma32(bf16x8 a, bf16x8 b, f32x16 c) { return __builtin_amdgcn_mfma_f32_32x32x16_bf16(a, b, c, 0, 0, 0); }
; __device__ __forceinline__ void store_tile16(bf16_t* p, const f32x16& a, float sc, int h) {
; #pragma unroll
;   for (int gp = 0; gp < 2; ++gp) {
;     u32x2 A = pack4(a[8 * gp] * sc, a[8 * gp + 1] * sc, a[8 * gp + 2] * sc, a[8 * gp + 3] * sc), B = pack4(a[8 * gp + 4] * sc, a[8 * gp + 5] * sc, a[8 * gp + 6] * sc, a[8 * gp + 7] * sc);
;     const auto r0 = __builtin_amdgcn_permlane32_swap(A[0], B[0], false, false), r1 = __builtin_amdgcn_permlane32_swap(A[1], B[1], false, false);
;     u32x4 o = {r0[0], r1[0], r0[1], r1[1]};
;     *(u32x4*)(p + 16 * gp + 8 * h) = o;
; __device__ void ret_state_item(const bf16_t* __restrict__ Kb, const bf16_t* __restrict__ Vb, bf16_t* __restrict__ STf, bf16_t* __restrict__ STb,
;                                int cidx, int head, float lgf2, float lgb2, LAS unsigned char* lds) {
;     ...
;   for (int ks = 0; ks < 8; ++ks) {
;     const unsigned r = (unsigned)(16 * ks + 8 * h + q4);
;     const bf16x8 Bv = tr_frag(lds, r * VS + w * 64 + cofs, (r + 4) * VS + w * 64 + cofs);
; #pragma unroll
;     for (int dt = 0; dt < 4; ++dt) {
;       const bf16x8 Af = tr_frag(lds, OKF + r * KS + dt * 64 + cofs, OKF + (r + 4) * KS + dt * 64 + cofs);
;       const bf16x8 Ab = tr_frag(lds, OKB + r * KS + dt * 64 + cofs, OKB + (r + 4) * KS + dt * 64 + cofs);
;       af[dt] = mfma32(Af, Bv, af[dt]); ab[dt] = mfma32(Ab, Bv, ab[dt]);
;     }
;   }
;   const size_t ob = ((size_t)(cidx * 4 + head) * 256 + w * 32 + (l & 31)) * 128;
; #pragma unroll
;   for (int dt = 0; dt < 4; ++dt) { store_tile16(STf + ob + dt * 32, af[dt], 1.f, h); store_tile16(STb + ob + dt * 32, ab[dt], 1.f, h); }
	v_mfma_f32_32x32x16_bf16 v[16:31], v[156:159], v[174:177], v[16:31]
	v_add_u32_e32 v156, 0x1ac00, v154
	v_add_u32_e32 v157, 0x24c00, v154
	v_add_u32_e32 v158, 0x25100, v154
	s_waitcnt lgkmcnt(2)
	v_mfma_f32_32x32x16_bf16 v[32:47], v[128:131], v[174:177], v[32:47]
	ds_read_b64_tr_b16 v[128:129], v156
	ds_read_b64_tr_b16 v[130:131], v155
	ds_read_b64_tr_b16 v[132:133], v132 offset:64512
	ds_read_b64_tr_b16 v[134:135], v134 offset:64512
	s_waitcnt lgkmcnt(4)
	v_mfma_f32_32x32x16_bf16 v[0:15], v[178:181], v[174:177], v[0:15]
	ds_read_b64_tr_b16 v[174:175], v157
	ds_read_b64_tr_b16 v[176:177], v158
	s_waitcnt lgkmcnt(2)
	v_mfma_f32_32x32x16_bf16 v[112:127], v[128:131], v[132:135], v[112:127]
	s_waitcnt lgkmcnt(0)
	v_mfma_f32_32x32x16_bf16 v[96:111], v[174:177], v[132:135], v[96:111]
	ds_read_b64_tr_b16 v[128:129], v156 offset:64
	ds_read_b64_tr_b16 v[130:131], v155 offset:64
	ds_read_b64_tr_b16 v[174:175], v157 offset:64
	ds_read_b64_tr_b16 v[176:177], v158 offset:64
	s_nop 5
	v_cvt_pk_bf16_f32 v112, v112, v113
	v_cvt_pk_bf16_f32 v113, v114, v115
	v_cvt_pk_bf16_f32 v114, v116, v117
	v_cvt_pk_bf16_f32 v115, v118, v119
	s_nop 0
	v_permlane32_swap_b32_e32 v112, v114
	s_waitcnt lgkmcnt(2)
	v_mfma_f32_32x32x16_bf16 v[80:95], v[128:131], v[132:135], v[80:95]
	v_cvt_pk_bf16_f32 v96, v96, v97
	v_cvt_pk_bf16_f32 v97, v98, v99
	v_cvt_pk_bf16_f32 v98, v100, v101
	v_cvt_pk_bf16_f32 v99, v102, v103
	v_permlane32_swap_b32_e32 v113, v115
	v_permlane32_swap_b32_e32 v96, v98
	s_waitcnt lgkmcnt(0)
	v_mfma_f32_32x32x16_bf16 v[64:79], v[174:177], v[132:135], v[64:79]
	ds_read_b64_tr_b16 v[128:129], v156 offset:128
	ds_read_b64_tr_b16 v[130:131], v155 offset:128
	ds_read_b64_tr_b16 v[174:175], v157 offset:128
	ds_read_b64_tr_b16 v[176:177], v158 offset:128
	v_cvt_pk_bf16_f32 v80, v80, v81
	v_cvt_pk_bf16_f32 v81, v82, v83
	v_cvt_pk_bf16_f32 v82, v84, v85
	v_cvt_pk_bf16_f32 v83, v86, v87
	v_permlane32_swap_b32_e32 v97, v99
	s_waitcnt lgkmcnt(2)
	v_mfma_f32_32x32x16_bf16 v[48:63], v[128:131], v[132:135], v[48:63]
	ds_read_b64_tr_b16 v[128:129], v156 offset:192
	ds_read_b64_tr_b16 v[130:131], v155 offset:192
	ds_read_b64_tr_b16 v[154:155], v157 offset:192
	ds_read_b64_tr_b16 v[156:157], v158 offset:192
	v_cvt_pk_bf16_f32 v64, v64, v65
	v_cvt_pk_bf16_f32 v65, v66, v67
	v_cvt_pk_bf16_f32 v66, v68, v69
	v_cvt_pk_bf16_f32 v67, v70, v71
	v_permlane32_swap_b32_e32 v80, v82
	s_waitcnt lgkmcnt(4)
	v_mfma_f32_32x32x16_bf16 v[16:31], v[174:177], v[132:135], v[16:31]
	s_nop 0
	v_cvt_pk_bf16_f32 v48, v48, v49
	v_cvt_pk_bf16_f32 v49, v50, v51
	v_cvt_pk_bf16_f32 v50, v52, v53
	v_cvt_pk_bf16_f32 v51, v54, v55
	v_permlane32_swap_b32_e32 v81, v83
	v_permlane32_swap_b32_e32 v64, v66
	s_waitcnt lgkmcnt(2)
	v_mfma_f32_32x32x16_bf16 v[32:47], v[128:131], v[132:135], v[32:47]
	v_ashrrev_i32_e32 v128, 1, v152
	v_and_b32_e32 v128, 0xffffffe0, v128
	v_ashrrev_i32_e32 v129, 31, v128
	v_or_b32_e32 v128, v128, v153
	v_lshl_add_u64 v[128:129], s[22:23], 0, v[128:129]
	v_lshlrev_b64 v[128:129], 8, v[128:129]
	v_lshl_add_u64 v[130:131], s[12:13], 0, v[128:129]
	s_waitcnt lgkmcnt(0)
	v_mfma_f32_32x32x16_bf16 v[0:15], v[154:157], v[132:135], v[0:15]
	v_readlane_b32 s12, v250, 53
	v_lshrrev_b32_e32 v132, 1, v152
	v_readlane_b32 s13, v250, 54
	v_and_b32_e32 v160, 16, v132
	v_cvt_pk_bf16_f32 v16, v16, v17
	v_lshl_add_u64 v[128:129], s[12:13], 0, v[128:129]
	v_cvt_pk_bf16_f32 v17, v18, v19
	v_cvt_pk_bf16_f32 v18, v20, v21
	v_cvt_pk_bf16_f32 v19, v22, v23
	v_lshl_add_u64 v[128:129], v[128:129], 0, v[160:161]
	v_permlane32_swap_b32_e32 v16, v18
	v_permlane32_swap_b32_e32 v17, v19
	s_barrier
; __device__ __forceinline__ u32x2 pack4(float a, float b, float c, float d) { u32x2 o; o[0] = cvt_pk_bf16(a, b); o[1] = cvt_pk_bf16(c, d); return o; }
; __device__ __forceinline__ void store_tile16(bf16_t* p, const f32x16& a, float sc, int h) {
; #pragma unroll
;   for (int gp = 0; gp < 2; ++gp) {
;     u32x2 A = pack4(a[8 * gp] * sc, a[8 * gp + 1] * sc, a[8 * gp + 2] * sc, a[8 * gp + 3] * sc), B = pack4(a[8 * gp + 4] * sc, a[8 * gp + 5] * sc, a[8 * gp + 6] * sc, a[8 * gp + 7] * sc);
;     const auto r0 = __builtin_amdgcn_permlane32_swap(A[0], B[0], false, false), r1 = __builtin_amdgcn_permlane32_swap(A[1], B[1], false, false);
;     u32x4 o = {r0[0], r1[0], r0[1], r1[1]};
;     *(u32x4*)(p + 16 * gp + 8 * h) = o;
; __device__ void ret_state_item(const bf16_t* __restrict__ Kb, const bf16_t* __restrict__ Vb, bf16_t* __restrict__ STf, bf16_t* __restrict__ STb,
;                                int cidx, int head, float lgf2, float lgb2, LAS unsigned char* lds) {
;     ...
;   const size_t ob = ((size_t)(cidx * 4 + head) * 256 + w * 32 + (l & 31)) * 128;
; #pragma unroll
;   for (int dt = 0; dt < 4; ++dt) { store_tile16(STf + ob + dt * 32, af[dt], 1.f, h); store_tile16(STb + ob + dt * 32, ab[dt], 1.f, h); }
;   __syncthreads();
	v_lshrrev_b32_e32 v176, 6, v152
	v_mul_u32_u24_e32 v176, 0x4400, v176
	v_mul_u32_u24_e32 v178, 0x110, v153
	v_add3_u32 v178, v176, v178, v160
	v_and_b32_e32 v179, 63, v152
	v_lshrrev_b32_e32 v188, 4, v179
	v_and_b32_e32 v189, 15, v179
	v_mul_u32_u24_e32 v188, 0x110, v188
	v_lshl_add_u32 v188, v189, 4, v188
	v_add_u32_e32 v190, v176, v188
	v_add_u32_e32 v191, 0x2200, v190
	v_mov_b32_e32 v176, v178
	v_add_u32_e32 v177, 0x2200, v176
	ds_write_b128 v177, v[16:19] offset:128
	v_readlane_b32 s12, v255, 34
	v_cvt_pk_bf16_f32 v0, v0, v1
	v_cvt_pk_bf16_f32 v16, v24, v25
	v_cvt_pk_bf16_f32 v17, v26, v27
	v_cvt_pk_bf16_f32 v18, v28, v29
	v_cvt_pk_bf16_f32 v19, v30, v31
	s_nop 0
	v_permlane32_swap_b32_e32 v16, v18
	v_permlane32_swap_b32_e32 v17, v19
	ds_write_b128 v177, v[16:19] offset:160
	v_cvt_pk_bf16_f32 v1, v2, v3
	v_cvt_pk_bf16_f32 v2, v4, v5
	v_cvt_pk_bf16_f32 v16, v32, v33
	v_cvt_pk_bf16_f32 v17, v34, v35
	v_cvt_pk_bf16_f32 v18, v36, v37
	v_cvt_pk_bf16_f32 v19, v38, v39
	v_cvt_pk_bf16_f32 v3, v6, v7
	s_add_i32 s6, s6, s12
	v_readlane_b32 s12, v255, 40
	v_lshl_add_u64 v[130:131], v[130:131], 0, v[160:161]
	v_permlane32_swap_b32_e32 v65, v67
	v_permlane32_swap_b32_e32 v48, v50
	v_permlane32_swap_b32_e32 v49, v51
	v_permlane32_swap_b32_e32 v16, v18
	v_permlane32_swap_b32_e32 v17, v19
	v_permlane32_swap_b32_e32 v0, v2
	v_permlane32_swap_b32_e32 v1, v3
	v_readlane_b32 s13, v255, 41
	s_add_u32 s22, s22, s12
	ds_write_b128 v176, v[112:115]
	ds_write_b128 v177, v[96:99]
	ds_write_b128 v176, v[80:83] offset:64
	v_cvt_pk_bf16_f32 v112, v120, v121
	v_cvt_pk_bf16_f32 v113, v122, v123
	v_cvt_pk_bf16_f32 v114, v124, v125
	v_cvt_pk_bf16_f32 v115, v126, v127
	v_cvt_pk_bf16_f32 v96, v104, v105
	v_cvt_pk_bf16_f32 v97, v106, v107
	v_cvt_pk_bf16_f32 v98, v108, v109
	v_cvt_pk_bf16_f32 v99, v110, v111
	v_cvt_pk_bf16_f32 v80, v88, v89
	v_cvt_pk_bf16_f32 v81, v90, v91
	v_cvt_pk_bf16_f32 v82, v92, v93
	v_cvt_pk_bf16_f32 v83, v94, v95
	ds_write_b128 v177, v[64:67] offset:64
	ds_write_b128 v176, v[48:51] offset:128
	ds_write_b128 v176, v[16:19] offset:192
	v_cvt_pk_bf16_f32 v64, v72, v73
	v_cvt_pk_bf16_f32 v65, v74, v75
	v_cvt_pk_bf16_f32 v66, v76, v77
	v_cvt_pk_bf16_f32 v67, v78, v79
	v_cvt_pk_bf16_f32 v48, v56, v57
	v_cvt_pk_bf16_f32 v49, v58, v59
	v_cvt_pk_bf16_f32 v50, v60, v61
	v_cvt_pk_bf16_f32 v51, v62, v63
	v_cvt_pk_bf16_f32 v16, v40, v41
	v_cvt_pk_bf16_f32 v17, v42, v43
	v_cvt_pk_bf16_f32 v18, v44, v45
	v_cvt_pk_bf16_f32 v19, v46, v47
	ds_write_b128 v177, v[0:3] offset:192
	s_addc_u32 s23, s23, s13
	v_permlane32_swap_b32_e32 v112, v114
	v_cvt_pk_bf16_f32 v0, v8, v9
	v_cvt_pk_bf16_f32 v1, v10, v11
	v_cvt_pk_bf16_f32 v2, v12, v13
	v_cvt_pk_bf16_f32 v3, v14, v15
	v_permlane32_swap_b32_e32 v113, v115
	v_permlane32_swap_b32_e32 v96, v98
	v_permlane32_swap_b32_e32 v97, v99
	v_permlane32_swap_b32_e32 v80, v82
	v_permlane32_swap_b32_e32 v81, v83
	v_permlane32_swap_b32_e32 v64, v66
	v_permlane32_swap_b32_e32 v65, v67
	v_permlane32_swap_b32_e32 v48, v50
	v_permlane32_swap_b32_e32 v49, v51
	v_permlane32_swap_b32_e32 v16, v18
	v_permlane32_swap_b32_e32 v17, v19
	v_permlane32_swap_b32_e32 v0, v2
	v_permlane32_swap_b32_e32 v1, v3
	s_cmpk_gt_i32 s7, 0x3ff
	ds_write_b128 v176, v[112:115] offset:32
	ds_write_b128 v177, v[96:99] offset:32
	ds_write_b128 v176, v[80:83] offset:96
	ds_write_b128 v177, v[64:67] offset:96
	ds_write_b128 v176, v[48:51] offset:160
	ds_write_b128 v176, v[16:19] offset:224
	ds_write_b128 v177, v[0:3] offset:224
	s_waitcnt lgkmcnt(0)
	v_lshlrev_b32_e32 v188, 4, v179
	v_lshlrev_b32_e32 v189, 8, v153
	v_sub_u32_e32 v188, v188, v189
	v_sub_u32_e32 v188, v188, v160
	v_ashrrev_i32_e32 v189, 31, v188
	v_lshl_add_u64 v[180:181], v[130:131], 0, v[188:189]
	v_lshl_add_u64 v[184:185], v[128:129], 0, v[188:189]
	s_mov_b32 s72, 0x1000
	s_mov_b32 s73, 0
	v_lshl_add_u64 v[182:183], v[180:181], 0, s[72:73]
	v_lshl_add_u64 v[186:187], v[184:185], 0, s[72:73]
	ds_read_b128 v[0:3], v190
	ds_read_b128 v[4:7], v190 offset:1088
	ds_read_b128 v[8:11], v190 offset:2176
	ds_read_b128 v[12:15], v190 offset:3264
	ds_read_b128 v[16:19], v190 offset:4352
	ds_read_b128 v[20:23], v190 offset:5440
	ds_read_b128 v[24:27], v190 offset:6528
	ds_read_b128 v[28:31], v190 offset:7616
	ds_read_b128 v[32:35], v191
	ds_read_b128 v[36:39], v191 offset:1088
	ds_read_b128 v[40:43], v191 offset:2176
	ds_read_b128 v[44:47], v191 offset:3264
	ds_read_b128 v[48:51], v191 offset:4352
	ds_read_b128 v[52:55], v191 offset:5440
	ds_read_b128 v[56:59], v191 offset:6528
	ds_read_b128 v[60:63], v191 offset:7616
	s_waitcnt lgkmcnt(15)
	global_store_dwordx4 v[180:181], v[0:3], off nt
	s_waitcnt lgkmcnt(14)
	global_store_dwordx4 v[180:181], v[4:7], off offset:1024 nt
	s_waitcnt lgkmcnt(13)
	global_store_dwordx4 v[180:181], v[8:11], off offset:2048 nt
	s_waitcnt lgkmcnt(12)
	global_store_dwordx4 v[180:181], v[12:15], off offset:3072 nt
	s_waitcnt lgkmcnt(11)
	global_store_dwordx4 v[182:183], v[16:19], off nt
	s_waitcnt lgkmcnt(10)
	global_store_dwordx4 v[182:183], v[20:23], off offset:1024 nt
	s_waitcnt lgkmcnt(9)
	global_store_dwordx4 v[182:183], v[24:27], off offset:2048 nt
	s_waitcnt lgkmcnt(8)
	global_store_dwordx4 v[182:183], v[28:31], off offset:3072 nt
	s_waitcnt lgkmcnt(7)
	global_store_dwordx4 v[184:185], v[32:35], off nt
	s_waitcnt lgkmcnt(6)
	global_store_dwordx4 v[184:185], v[36:39], off offset:1024 nt
	s_waitcnt lgkmcnt(5)
	global_store_dwordx4 v[184:185], v[40:43], off offset:2048 nt
	s_waitcnt lgkmcnt(4)
	global_store_dwordx4 v[184:185], v[44:47], off offset:3072 nt
	s_waitcnt lgkmcnt(3)
	global_store_dwordx4 v[186:187], v[48:51], off nt
	s_waitcnt lgkmcnt(2)
	global_store_dwordx4 v[186:187], v[52:55], off offset:1024 nt
	s_waitcnt lgkmcnt(1)
	global_store_dwordx4 v[186:187], v[56:59], off offset:2048 nt
	s_waitcnt lgkmcnt(0)
	global_store_dwordx4 v[186:187], v[60:63], off offset:3072 nt
	s_barrier
	s_cbranch_scc1 .LBB0_429
